# v1 plus final-RMSNorm and x-to-bf16 row loads batched
# baseline (speedup 1.0000x reference)
.LBB0_404:
	s_and_b64 vcc, exec, s[16:17]
	s_cbranch_vccz .LBB0_409
	v_mov_b32_e32 v1, v220
	v_readlane_b32 s12, v244, 18
	v_ashrrev_i32_e32 v2, 6, v1
	s_nop 0
	v_add_u32_e32 v2, s12, v2
	s_movk_i32 s12, 0x2000
	v_cmp_gt_i32_e32 vcc, s12, v2
	s_and_saveexec_b64 s[16:17], vcc
	s_cbranch_execz .LBB0_408
	v_and_b32_e32 v1, 63, v1
	v_readlane_b32 s24, v246, 4
	v_readlane_b32 s25, v246, 5
	v_readlane_b32 s26, v246, 6
	v_readlane_b32 s27, v246, 7
	s_add_u32 s20, s76, 0x2c184000
	s_addc_u32 s21, s77, 0
	s_add_u32 s22, s76, 0x11080000
	s_addc_u32 s23, s77, 0
	v_lshlrev_b32_e32 v3, 4, v1
	v_add_u32_e32 v4, 0x1000, v3
	s_waitcnt lgkmcnt(0)
	s_nop 1
	global_load_dwordx4 v[32:35], v3, s[24:25]
	global_load_dwordx4 v[36:39], v3, s[24:25] offset:1024
	global_load_dwordx4 v[40:43], v3, s[24:25] offset:2048
	global_load_dwordx4 v[44:47], v3, s[24:25] offset:3072
	global_load_dwordx4 v[48:51], v4, s[24:25]
	global_load_dwordx4 v[52:55], v4, s[24:25] offset:1024
	global_load_dwordx4 v[56:59], v4, s[24:25] offset:2048
	global_load_dwordx4 v[60:63], v4, s[24:25] offset:3072
	v_lshlrev_b32_e32 v5, 2, v2
	v_lshlrev_b32_e32 v6, 12, v2
	v_lshl_or_b32 v6, v1, 3, v6
	v_lshlrev_b32_e32 v7, 13, v2
	v_or_b32_e32 v7, v7, v3
	s_mov_b64 s[18:19], 0
.LBB0_407:
	global_load_dword v64, v5, s[20:21]
	v_add_u32_e32 v8, 0x8000, v5
	global_load_dword v65, v8, s[20:21]
	v_add_u32_e32 v9, 0x10000, v5
	global_load_dword v66, v9, s[20:21]
	v_add_u32_e32 v10, 0x18000, v5
	global_load_dword v67, v10, s[20:21]
	v_add_u32_e32 v11, 0x20000, v5
	global_load_dword v68, v11, s[20:21]
	v_add_u32_e32 v12, 0x28000, v5
	global_load_dword v69, v12, s[20:21]
	v_add_u32_e32 v13, 0x30000, v5
	global_load_dword v70, v13, s[20:21]
	v_add_u32_e32 v14, 0x38000, v5
	global_load_dword v71, v14, s[20:21]
	global_load_dwordx2 v[72:73], v6, s[22:23]
	global_load_dwordx2 v[74:75], v6, s[22:23] offset:512
	global_load_dwordx2 v[76:77], v6, s[22:23] offset:1024
	global_load_dwordx2 v[78:79], v6, s[22:23] offset:1536
	global_load_dwordx2 v[80:81], v6, s[22:23] offset:2048
	global_load_dwordx2 v[82:83], v6, s[22:23] offset:2560
	global_load_dwordx2 v[84:85], v6, s[22:23] offset:3072
	global_load_dwordx2 v[86:87], v6, s[22:23] offset:3584
	v_add_u32_e32 v2, s10, v2
	v_add_u32_e32 v15, 0x1000, v7
	v_cmp_lt_i32_e32 vcc, s68, v2
	s_or_b64 s[18:19], vcc, s[18:19]
	s_waitcnt vmcnt(8)
	v_add_f32_e32 v20, 0, v64
	v_add_f32_e32 v20, v20, v65
	v_add_f32_e32 v20, v20, v66
	v_add_f32_e32 v20, v20, v67
	v_add_f32_e32 v20, v20, v68
	v_add_f32_e32 v20, v20, v69
	v_add_f32_e32 v20, v20, v70
	v_add_f32_e32 v20, v20, v71
	v_fmamk_f32 v20, v20, 0x3a000000, v223
	v_cmp_gt_f32_e32 vcc, s4, v20
	v_mul_f32_e32 v21, 0x4b800000, v20
	s_nop 0
	v_cndmask_b32_e32 v20, v20, v21, vcc
	v_rsq_f32_e32 v20, v20
	s_nop 0
	v_mul_f32_e32 v21, 0x45800000, v20
	v_cndmask_b32_e32 v20, v20, v21, vcc
	s_waitcnt vmcnt(7)
	v_lshlrev_b32_e32 v28, 16, v72
	v_and_b32_e32 v29, 0xffff0000, v72
	v_lshlrev_b32_e32 v30, 16, v73
	v_and_b32_e32 v31, 0xffff0000, v73
	v_pk_mul_f32 v[28:29], v[20:21], v[28:29] op_sel_hi:[0,1]
	v_pk_mul_f32 v[30:31], v[20:21], v[30:31] op_sel_hi:[0,1]
	v_pk_mul_f32 v[24:25], v[32:33], v[28:29]
	v_pk_mul_f32 v[26:27], v[34:35], v[30:31]
	global_store_dwordx4 v7, v[24:27], s[26:27]
	s_waitcnt vmcnt(7)
	v_lshlrev_b32_e32 v92, 16, v74
	v_and_b32_e32 v93, 0xffff0000, v74
	v_lshlrev_b32_e32 v94, 16, v75
	v_and_b32_e32 v95, 0xffff0000, v75
	v_pk_mul_f32 v[92:93], v[20:21], v[92:93] op_sel_hi:[0,1]
	v_pk_mul_f32 v[94:95], v[20:21], v[94:95] op_sel_hi:[0,1]
	v_pk_mul_f32 v[88:89], v[36:37], v[92:93]
	v_pk_mul_f32 v[90:91], v[38:39], v[94:95]
	global_store_dwordx4 v7, v[88:91], s[26:27] offset:1024
	s_waitcnt vmcnt(7)
	v_lshlrev_b32_e32 v28, 16, v76
	v_and_b32_e32 v29, 0xffff0000, v76
	v_lshlrev_b32_e32 v30, 16, v77
	v_and_b32_e32 v31, 0xffff0000, v77
	v_pk_mul_f32 v[28:29], v[20:21], v[28:29] op_sel_hi:[0,1]
	v_pk_mul_f32 v[30:31], v[20:21], v[30:31] op_sel_hi:[0,1]
	v_pk_mul_f32 v[24:25], v[40:41], v[28:29]
	v_pk_mul_f32 v[26:27], v[42:43], v[30:31]
	global_store_dwordx4 v7, v[24:27], s[26:27] offset:2048
	s_waitcnt vmcnt(7)
	v_lshlrev_b32_e32 v92, 16, v78
	v_and_b32_e32 v93, 0xffff0000, v78
	v_lshlrev_b32_e32 v94, 16, v79
	v_and_b32_e32 v95, 0xffff0000, v79
	v_pk_mul_f32 v[92:93], v[20:21], v[92:93] op_sel_hi:[0,1]
	v_pk_mul_f32 v[94:95], v[20:21], v[94:95] op_sel_hi:[0,1]
	v_pk_mul_f32 v[88:89], v[44:45], v[92:93]
	v_pk_mul_f32 v[90:91], v[46:47], v[94:95]
	global_store_dwordx4 v7, v[88:91], s[26:27] offset:3072
	s_waitcnt vmcnt(7)
	v_lshlrev_b32_e32 v28, 16, v80
	v_and_b32_e32 v29, 0xffff0000, v80
	v_lshlrev_b32_e32 v30, 16, v81
	v_and_b32_e32 v31, 0xffff0000, v81
	v_pk_mul_f32 v[28:29], v[20:21], v[28:29] op_sel_hi:[0,1]
	v_pk_mul_f32 v[30:31], v[20:21], v[30:31] op_sel_hi:[0,1]
	v_pk_mul_f32 v[24:25], v[48:49], v[28:29]
	v_pk_mul_f32 v[26:27], v[50:51], v[30:31]
	global_store_dwordx4 v15, v[24:27], s[26:27]
	s_waitcnt vmcnt(7)
	v_lshlrev_b32_e32 v92, 16, v82
	v_and_b32_e32 v93, 0xffff0000, v82
	v_lshlrev_b32_e32 v94, 16, v83
	v_and_b32_e32 v95, 0xffff0000, v83
	v_pk_mul_f32 v[92:93], v[20:21], v[92:93] op_sel_hi:[0,1]
	v_pk_mul_f32 v[94:95], v[20:21], v[94:95] op_sel_hi:[0,1]
	v_pk_mul_f32 v[88:89], v[52:53], v[92:93]
	v_pk_mul_f32 v[90:91], v[54:55], v[94:95]
	global_store_dwordx4 v15, v[88:91], s[26:27] offset:1024
	s_waitcnt vmcnt(7)
	v_lshlrev_b32_e32 v28, 16, v84
	v_and_b32_e32 v29, 0xffff0000, v84
	v_lshlrev_b32_e32 v30, 16, v85
	v_and_b32_e32 v31, 0xffff0000, v85
	v_pk_mul_f32 v[28:29], v[20:21], v[28:29] op_sel_hi:[0,1]
	v_pk_mul_f32 v[30:31], v[20:21], v[30:31] op_sel_hi:[0,1]
	v_pk_mul_f32 v[24:25], v[56:57], v[28:29]
	v_pk_mul_f32 v[26:27], v[58:59], v[30:31]
	global_store_dwordx4 v15, v[24:27], s[26:27] offset:2048
	s_waitcnt vmcnt(7)
	v_lshlrev_b32_e32 v92, 16, v86
	v_and_b32_e32 v93, 0xffff0000, v86
	v_lshlrev_b32_e32 v94, 16, v87
	v_and_b32_e32 v95, 0xffff0000, v87
	v_pk_mul_f32 v[92:93], v[20:21], v[92:93] op_sel_hi:[0,1]
	v_pk_mul_f32 v[94:95], v[20:21], v[94:95] op_sel_hi:[0,1]
	v_pk_mul_f32 v[88:89], v[60:61], v[92:93]
	v_pk_mul_f32 v[90:91], v[62:63], v[94:95]
	global_store_dwordx4 v15, v[88:91], s[26:27] offset:3072
	v_add_u32_e32 v5, s74, v5
	v_add_u32_e32 v6, s98, v6
	v_add_u32_e32 v7, s70, v7
	s_andn2_b64 exec, exec, s[18:19]
	s_cbranch_execnz .LBB0_407
.LBB0_408:
	s_or_b64 exec, exec, s[16:17]
	v_readlane_b32 s20, v246, 0
	v_readlane_b32 s21, v246, 1
	v_readlane_b32 s22, v246, 2
	v_readlane_b32 s23, v246, 3
	v_readlane_b32 s24, v246, 4
	v_readlane_b32 s26, v246, 6
	v_readlane_b32 s27, v246, 7
	s_mov_b32 s25, 0x10000

.LBB0_458:
	global_load_dwordx4 v[68:71], v[2:3], off offset:-4096
	global_load_dwordx4 v[72:75], v[2:3], off offset:-3072
	global_load_dwordx4 v[76:79], v[2:3], off offset:-2048
	global_load_dwordx4 v[80:83], v[2:3], off offset:-1024
	global_load_dwordx4 v[84:87], v[2:3], off
	global_load_dwordx4 v[88:91], v[2:3], off offset:1024
	global_load_dwordx4 v[92:95], v[2:3], off offset:2048
	global_load_dwordx4 v[96:99], v[2:3], off offset:3072
	s_waitcnt lgkmcnt(0)
	s_waitcnt vmcnt(7)
	v_mul_f32_e32 v1, v69, v69
	v_fmac_f32_e32 v1, v68, v68
	v_mul_f32_e32 v7, v71, v71
	v_cvt_pk_bf16_f32 v8, v68, v69
	v_cvt_pk_bf16_f32 v9, v70, v71
	global_store_dwordx2 v[4:5], v[8:9], off
	v_fmac_f32_e32 v7, v70, v70
	v_add_f32_e32 v1, v1, v7
	s_waitcnt vmcnt(7)
	v_mul_f32_e32 v7, v73, v73
	v_fmac_f32_e32 v7, v72, v72
	v_mul_f32_e32 v12, v75, v75
	v_cvt_pk_bf16_f32 v10, v72, v73
	v_cvt_pk_bf16_f32 v11, v74, v75
	global_store_dwordx2 v[4:5], v[10:11], off offset:512
	v_fmac_f32_e32 v12, v74, v74
	v_add_f32_e32 v7, v7, v12
	v_add_f32_e32 v1, v1, v7
	s_waitcnt vmcnt(7)
	v_mul_f32_e32 v7, v77, v77
	v_fmac_f32_e32 v7, v76, v76
	v_mul_f32_e32 v12, v79, v79
	v_cvt_pk_bf16_f32 v8, v76, v77
	v_cvt_pk_bf16_f32 v9, v78, v79
	global_store_dwordx2 v[4:5], v[8:9], off offset:1024
	v_fmac_f32_e32 v12, v78, v78
	v_add_f32_e32 v7, v7, v12
	v_add_f32_e32 v1, v1, v7
	s_waitcnt vmcnt(7)
	v_mul_f32_e32 v7, v81, v81
	v_fmac_f32_e32 v7, v80, v80
	v_mul_f32_e32 v12, v83, v83
	v_cvt_pk_bf16_f32 v10, v80, v81
	v_cvt_pk_bf16_f32 v11, v82, v83
	global_store_dwordx2 v[4:5], v[10:11], off offset:1536
	v_fmac_f32_e32 v12, v82, v82
	v_add_f32_e32 v7, v7, v12
	v_add_f32_e32 v1, v1, v7
	s_waitcnt vmcnt(7)
	v_mul_f32_e32 v7, v85, v85
	v_fmac_f32_e32 v7, v84, v84
	v_mul_f32_e32 v12, v87, v87
	v_cvt_pk_bf16_f32 v8, v84, v85
	v_cvt_pk_bf16_f32 v9, v86, v87
	global_store_dwordx2 v[4:5], v[8:9], off offset:2048
	v_fmac_f32_e32 v12, v86, v86
	v_add_f32_e32 v7, v7, v12
	v_add_f32_e32 v1, v1, v7
	s_waitcnt vmcnt(7)
	v_mul_f32_e32 v7, v89, v89
	v_fmac_f32_e32 v7, v88, v88
	v_mul_f32_e32 v12, v91, v91
	v_cvt_pk_bf16_f32 v10, v88, v89
	v_cvt_pk_bf16_f32 v11, v90, v91
	global_store_dwordx2 v[4:5], v[10:11], off offset:2560
	v_fmac_f32_e32 v12, v90, v90
	v_add_f32_e32 v7, v7, v12
	v_add_f32_e32 v1, v1, v7
	s_waitcnt vmcnt(7)
	v_mul_f32_e32 v7, v93, v93
	v_fmac_f32_e32 v7, v92, v92
	v_mul_f32_e32 v12, v95, v95
	v_cvt_pk_bf16_f32 v8, v92, v93
	v_cvt_pk_bf16_f32 v9, v94, v95
	global_store_dwordx2 v[4:5], v[8:9], off offset:3072
	v_fmac_f32_e32 v12, v94, v94
	v_add_f32_e32 v7, v7, v12
	v_add_f32_e32 v1, v1, v7
	s_waitcnt vmcnt(7)
	v_mul_f32_e32 v7, v97, v97
	v_fmac_f32_e32 v7, v96, v96
	v_mul_f32_e32 v12, v99, v99
	v_cvt_pk_bf16_f32 v10, v96, v97
	v_cvt_pk_bf16_f32 v11, v98, v99
	global_store_dwordx2 v[4:5], v[10:11], off offset:3584
	v_fmac_f32_e32 v12, v98, v98
	v_add_f32_e32 v7, v7, v12
	v_add_f32_e32 v1, v1, v7
	v_and_b32_e32 v7, 64, v222
	v_add_u32_e32 v7, 64, v7
	v_xor_b32_e32 v8, 1, v222
	v_cmp_lt_i32_e64 s[40:41], v8, v7
	s_nop 1
	v_cndmask_b32_e64 v8, v222, v8, s[40:41]
	v_lshlrev_b32_e32 v8, 2, v8
	ds_bpermute_b32 v8, v8, v1
	s_waitcnt lgkmcnt(0)
	v_add_f32_e32 v1, v1, v8
	v_xor_b32_e32 v8, 2, v222
	v_cmp_lt_i32_e64 s[40:41], v8, v7
	s_nop 1
	v_cndmask_b32_e64 v8, v222, v8, s[40:41]
	v_lshlrev_b32_e32 v8, 2, v8
	ds_bpermute_b32 v8, v8, v1
	s_waitcnt lgkmcnt(0)
	v_add_f32_e32 v1, v1, v8
	v_xor_b32_e32 v8, 4, v222
	v_cmp_lt_i32_e64 s[40:41], v8, v7
	s_nop 1
	v_cndmask_b32_e64 v8, v222, v8, s[40:41]
	v_lshlrev_b32_e32 v8, 2, v8
	ds_bpermute_b32 v8, v8, v1
	s_waitcnt lgkmcnt(0)
	v_add_f32_e32 v1, v1, v8
	v_xor_b32_e32 v8, 8, v222
	v_cmp_lt_i32_e64 s[40:41], v8, v7
	s_nop 1
	v_cndmask_b32_e64 v8, v222, v8, s[40:41]
	v_lshlrev_b32_e32 v8, 2, v8
	ds_bpermute_b32 v8, v8, v1
	s_waitcnt lgkmcnt(0)
	v_add_f32_e32 v1, v1, v8
	v_xor_b32_e32 v8, 16, v222
	v_cmp_lt_i32_e64 s[40:41], v8, v7
	s_nop 1
	v_cndmask_b32_e64 v8, v222, v8, s[40:41]
	v_lshlrev_b32_e32 v8, 2, v8
	ds_bpermute_b32 v8, v8, v1
	s_waitcnt lgkmcnt(0)
	v_add_f32_e32 v1, v1, v8
	v_xor_b32_e32 v8, 32, v222
	v_cmp_lt_i32_e64 s[40:41], v8, v7
	s_nop 1
	v_cndmask_b32_e64 v7, v222, v8, s[40:41]
	v_lshlrev_b32_e32 v7, 2, v7
	ds_bpermute_b32 v7, v7, v1
	s_and_saveexec_b64 s[20:21], vcc
	s_cbranch_execz .LBB0_457
	v_add_u32_e32 v8, v6, v66
	s_waitcnt lgkmcnt(0)
	v_add_f32_e32 v1, v1, v7
	v_ashrrev_i32_e32 v9, 31, v8
	v_cndmask_b32_e64 v1, 0, v1, s[38:39]
	v_lshl_add_u64 v[8:9], v[8:9], 2, s[0:1]
	global_store_dword v[8:9], v1, off
	s_branch .LBB0_457
